# attention: s_setprio 1 moved ahead of the lgkmcnt wait and barrier so the compute segment opens directly with its first MFMA (pure reorder, addresses unchanged)
# speedup vs baseline: 1.0142x; 1.0015x over previous
; DI unsigned pack2(float a, float b) { f32x2_t v = {a, b}; bf16x2_t r = __builtin_convertvector(v, bf16x2_t); return __builtin_bit_cast(unsigned, r); }
; #define LOADT(key0) do { kr0 = *(const uint4*)(Kp + (size_t)((key0) + krow0) * ldk + kch0 * 8); \
;     if (k2) kr1 = *(const uint4*)(Kp + (size_t)((key0) + krow1) * ldk + kch1 * 8); \
;     vr = *(const uint4*)(Vt + (size_t)vrow * S_ + (key0) + vch * 8); } while (0)
; #define STORET(bufi) do { char* bb = smem + (bufi) * BUF; *(uint4*)(bb + krow0 * KS + kch0 * 16) = kr0; \
;     if (k2) *(uint4*)(bb + krow1 * KS + kch1 * 16) = kr1; \
;     *(uint4*)(bb + KB + vrow * VS + vch * 16) = vr; } while (0)
; #define BARX do { __builtin_amdgcn_sched_barrier(0); asm volatile("s_waitcnt lgkmcnt(0)" ::: "memory"); __builtin_amdgcn_s_barrier(); __builtin_amdgcn_sched_barrier(0); } while (0)
; template <int D>
; DI void attn_tile(const u16* __restrict__ Qp, int ldq, const u16* __restrict__ Kp, int ldk, const u16* __restrict__ Vt,
;                   u16* __restrict__ Op, int ldo, int q0, float cs, float mc) {
;     ...
;     bf16x8 pf[2][2];
;     if (mc != 0.f) {
; #pragma unroll
;       for (int i = 0; i < 16; ++i) { s0[i] -= mc; s1[i] -= mc; }
;     }
; #pragma unroll
;     for (int i = 0; i < 16; ++i) {
;       s0[i] = __builtin_amdgcn_exp2f(s0[i]); s1[i] = __builtin_amdgcn_exp2f(s1[i]);
;       lsum0 += s0[i]; lsum1 += s1[i];
;     }
; #pragma unroll
;     for (int st = 0; st < 2; ++st) {
;       uint4 a = {pack2(s0[8 * st], s0[8 * st + 1]), pack2(s0[8 * st + 2], s0[8 * st + 3]), pack2(s0[8 * st + 4], s0[8 * st + 5]), pack2(s0[8 * st + 6], s0[8 * st + 7])};
;       uint4 c = {pack2(s1[8 * st], s1[8 * st + 1]), pack2(s1[8 * st + 2], s1[8 * st + 3]), pack2(s1[8 * st + 4], s1[8 * st + 5]), pack2(s1[8 * st + 6], s1[8 * st + 7])};
;       pf[0][st] = __builtin_bit_cast(bf16x8, a); pf[1][st] = __builtin_bit_cast(bf16x8, c);
;     }
;     if (it + 2 < NIT) STORET((it + 2) & 3);
;     if (it + 3 < NIT) LOADT((it + 3) * 64);
;     if (it + 1 < NIT) LOADKF((it + 1) & 3);
;     BARX;
;     __builtin_amdgcn_s_setprio(1);
;     {
;       const char* vb = smem + (it & 3) * BUF + KB + r * VS + 16 * hh;
;       bf16x8 v0[2], v1[2];
; #pragma unroll
;       for (int q = 0; q < 2; ++q) { v0[q] = *(const bf16x8*)(vb + 32 * q); v1[q] = *(const bf16x8*)(vb + 32 * VS + 32 * q); }
;       if (it + 1 < NIT) SMMA();
.LBB0_198:
	s_and_b32 s44, s36, 3
	s_mulk_i32 s44, 0x5800
	v_add_u32_e32 v226, s44, v249
	ds_read_b128 v[128:131], v226
	ds_read_b128 v[132:135], v226 offset:32
	ds_read_b128 v[140:143], v226 offset:6656
	ds_read_b128 v[144:147], v226 offset:6688
	ds_read_b128 v[148:151], v226 offset:64
	ds_read_b128 v[152:155], v226 offset:96
	ds_read_b128 v[156:159], v226 offset:6720
	ds_read_b128 v[160:163], v226 offset:6752
	ds_read_b128 v[164:167], v226 offset:128
	ds_read_b128 v[168:171], v226 offset:160
	ds_read_b128 v[172:175], v226 offset:6784
	ds_read_b128 v[176:179], v226 offset:6816
	s_and_b32 s10, s37, 3
	s_mulk_i32 s10, 0x5800
	v_add_u32_e32 v201, s10, v196
	s_setprio 1
	s_waitcnt lgkmcnt(0)
	s_barrier
	v_mfma_f32_32x32x16_bf16 v[32:47], v[128:131], v[96:99], 0
	ds_read_b128 v[188:191], v201 offset:13312
	ds_read_b128 v[192:195], v201 offset:17920
	v_cvt_pk_bf16_f32 v210, v64, v65
	v_cvt_pk_bf16_f32 v211, v66, v67
	v_cvt_pk_bf16_f32 v212, v68, v69
	v_cvt_pk_bf16_f32 v213, v70, v71
	v_mfma_f32_32x32x16_bf16 v[48:63], v[140:143], v[96:99], 0
	ds_read_b128 v[184:187], v201 offset:13344
	ds_read_b128 v[180:183], v201 offset:17952
	v_cvt_pk_bf16_f32 v214, v72, v73
	v_cvt_pk_bf16_f32 v215, v74, v75
	v_cvt_pk_bf16_f32 v216, v76, v77
	v_cvt_pk_bf16_f32 v217, v78, v79
	v_mfma_f32_32x32x16_bf16 v[32:47], v[132:135], v[100:103], v[32:47]
	v_cvt_pk_bf16_f32 v218, v80, v81
	v_cvt_pk_bf16_f32 v219, v82, v83
	v_cvt_pk_bf16_f32 v220, v84, v85
	v_cvt_pk_bf16_f32 v221, v86, v87
	v_mfma_f32_32x32x16_bf16 v[48:63], v[144:147], v[100:103], v[48:63]
	v_cvt_pk_bf16_f32 v222, v88, v89
	v_cvt_pk_bf16_f32 v223, v90, v91
	v_cvt_pk_bf16_f32 v224, v92, v93
	v_cvt_pk_bf16_f32 v225, v94, v95
	v_mfma_f32_32x32x16_bf16 v[32:47], v[148:151], v[104:107], v[32:47]
	v_add_f32_e32 v208, v64, v208
	v_add_f32_e32 v209, v80, v209
	v_add_f32_e32 v208, v65, v208
	v_add_f32_e32 v209, v81, v209
	v_mfma_f32_32x32x16_bf16 v[48:63], v[156:159], v[104:107], v[48:63]
	v_add_f32_e32 v208, v66, v208
	v_add_f32_e32 v209, v82, v209
	v_add_f32_e32 v208, v67, v208
	v_add_f32_e32 v209, v83, v209
	v_mfma_f32_32x32x16_bf16 v[32:47], v[152:155], v[108:111], v[32:47]
	v_add_f32_e32 v208, v68, v208
	v_add_f32_e32 v209, v84, v209
	v_add_f32_e32 v208, v69, v208
	v_add_f32_e32 v209, v85, v209
	v_mfma_f32_32x32x16_bf16 v[48:63], v[160:163], v[108:111], v[48:63]
	v_add_f32_e32 v208, v70, v208
	v_add_f32_e32 v209, v86, v209
	v_add_f32_e32 v208, v71, v208
	v_add_f32_e32 v209, v87, v209
	v_mfma_f32_32x32x16_bf16 v[32:47], v[164:167], v[112:115], v[32:47]
	v_add_f32_e32 v208, v72, v208
	v_add_f32_e32 v209, v88, v209
	v_add_f32_e32 v208, v73, v208
	v_add_f32_e32 v209, v89, v209
	v_mfma_f32_32x32x16_bf16 v[48:63], v[172:175], v[112:115], v[48:63]
	v_add_f32_e32 v208, v74, v208
	v_add_f32_e32 v209, v90, v209
	v_add_f32_e32 v208, v75, v208
	v_add_f32_e32 v209, v91, v209
	v_mfma_f32_32x32x16_bf16 v[32:47], v[168:171], v[116:119], v[32:47]
	v_add_f32_e32 v208, v76, v208
	v_add_f32_e32 v209, v92, v209
	v_add_f32_e32 v208, v77, v208
	v_add_f32_e32 v209, v93, v209
	v_mfma_f32_32x32x16_bf16 v[48:63], v[176:179], v[116:119], v[48:63]
	v_add_f32_e32 v208, v78, v208
	v_add_f32_e32 v209, v94, v209
	v_add_f32_e32 v208, v79, v208
	v_add_f32_e32 v209, v95, v209
	ds_read_b128 v[140:143], v201 offset:13376
	ds_read_b128 v[144:147], v201 offset:17984
	ds_read_b128 v[148:151], v201 offset:13408
	ds_read_b128 v[152:155], v201 offset:18016
	s_andn2_b64 vcc, exec, s[38:39]
	s_cbranch_vccnz .LBB0_190
	s_nop 3
	v_sub_f32_e32 v47, v47, v232
	v_sub_f32_e32 v46, v46, v232
	v_sub_f32_e32 v45, v45, v232
	v_sub_f32_e32 v44, v44, v232
	v_sub_f32_e32 v43, v43, v232
	v_sub_f32_e32 v42, v42, v232
	v_sub_f32_e32 v41, v41, v232
	v_sub_f32_e32 v40, v40, v232
	v_sub_f32_e32 v39, v39, v232
	v_sub_f32_e32 v38, v38, v232
	v_sub_f32_e32 v37, v37, v232
	v_sub_f32_e32 v36, v36, v232
	v_sub_f32_e32 v35, v35, v232
	v_sub_f32_e32 v34, v34, v232
	v_sub_f32_e32 v33, v33, v232
	v_sub_f32_e32 v32, v32, v232
	v_sub_f32_e32 v63, v63, v232
	v_sub_f32_e32 v62, v62, v232
	v_sub_f32_e32 v61, v61, v232
	v_sub_f32_e32 v60, v60, v232
	v_sub_f32_e32 v59, v59, v232
	v_sub_f32_e32 v58, v58, v232
	v_sub_f32_e32 v57, v57, v232
	v_sub_f32_e32 v56, v56, v232
	v_sub_f32_e32 v55, v55, v232
	v_sub_f32_e32 v54, v54, v232
	v_sub_f32_e32 v53, v53, v232
	v_sub_f32_e32 v52, v52, v232
	v_sub_f32_e32 v51, v51, v232
	v_sub_f32_e32 v50, v50, v232
	v_sub_f32_e32 v49, v49, v232
	v_sub_f32_e32 v48, v48, v232

; DI unsigned pack2(float a, float b) { f32x2_t v = {a, b}; bf16x2_t r = __builtin_convertvector(v, bf16x2_t); return __builtin_bit_cast(unsigned, r); }
; #define LOADT(key0) do { kr0 = *(const uint4*)(Kp + (size_t)((key0) + krow0) * ldk + kch0 * 8); \
;     if (k2) kr1 = *(const uint4*)(Kp + (size_t)((key0) + krow1) * ldk + kch1 * 8); \
;     vr = *(const uint4*)(Vt + (size_t)vrow * S_ + (key0) + vch * 8); } while (0)
; #define STORET(bufi) do { char* bb = smem + (bufi) * BUF; *(uint4*)(bb + krow0 * KS + kch0 * 16) = kr0; \
;     if (k2) *(uint4*)(bb + krow1 * KS + kch1 * 16) = kr1; \
;     *(uint4*)(bb + KB + vrow * VS + vch * 16) = vr; } while (0)
; #define BARX do { __builtin_amdgcn_sched_barrier(0); asm volatile("s_waitcnt lgkmcnt(0)" ::: "memory"); __builtin_amdgcn_s_barrier(); __builtin_amdgcn_sched_barrier(0); } while (0)
; template <int D>
; DI void attn_tile(const u16* __restrict__ Qp, int ldq, const u16* __restrict__ Kp, int ldk, const u16* __restrict__ Vt,
;                   u16* __restrict__ Op, int ldo, int q0, float cs, float mc) {
;     ...
;     bf16x8 pf[2][2];
;     if (mc != 0.f) {
; #pragma unroll
;       for (int i = 0; i < 16; ++i) { s0[i] -= mc; s1[i] -= mc; }
;     }
; #pragma unroll
;     for (int i = 0; i < 16; ++i) {
;       s0[i] = __builtin_amdgcn_exp2f(s0[i]); s1[i] = __builtin_amdgcn_exp2f(s1[i]);
;       lsum0 += s0[i]; lsum1 += s1[i];
;     }
; #pragma unroll
;     for (int st = 0; st < 2; ++st) {
;       uint4 a = {pack2(s0[8 * st], s0[8 * st + 1]), pack2(s0[8 * st + 2], s0[8 * st + 3]), pack2(s0[8 * st + 4], s0[8 * st + 5]), pack2(s0[8 * st + 6], s0[8 * st + 7])};
;       uint4 c = {pack2(s1[8 * st], s1[8 * st + 1]), pack2(s1[8 * st + 2], s1[8 * st + 3]), pack2(s1[8 * st + 4], s1[8 * st + 5]), pack2(s1[8 * st + 6], s1[8 * st + 7])};
;       pf[0][st] = __builtin_bit_cast(bf16x8, a); pf[1][st] = __builtin_bit_cast(bf16x8, c);
;     }
;     if (it + 2 < NIT) STORET((it + 2) & 3);
;     if (it + 3 < NIT) LOADT((it + 3) * 64);
;     if (it + 1 < NIT) LOADKF((it + 1) & 3);
;     BARX;
;     __builtin_amdgcn_s_setprio(1);
;     {
;       const char* vb = smem + (it & 3) * BUF + KB + r * VS + 16 * hh;
;       bf16x8 v0[2], v1[2];
; #pragma unroll
;       for (int q = 0; q < 2; ++q) { v0[q] = *(const bf16x8*)(vb + 32 * q); v1[q] = *(const bf16x8*)(vb + 32 * VS + 32 * q); }
;       if (it + 1 < NIT) SMMA();
.LBB0_836:
	s_and_b32 s40, s36, 3
	s_mulk_i32 s40, 0x4800
	v_add_u32_e32 v192, s40, v204
	ds_read_b128 v[120:123], v192
	ds_read_b128 v[124:127], v192 offset:32
	ds_read_b128 v[128:131], v192 offset:4608
	ds_read_b128 v[132:135], v192 offset:4640
	ds_read_b128 v[136:139], v192 offset:64
	ds_read_b128 v[140:143], v192 offset:96
	ds_read_b128 v[144:147], v192 offset:4672
	ds_read_b128 v[148:151], v192 offset:4704
	s_and_b32 s10, s37, 3
	s_mulk_i32 s10, 0x4800
	v_add_u32_e32 v196, s10, v204
	s_setprio 1
	s_waitcnt lgkmcnt(0)
	s_barrier
	v_mfma_f32_32x32x16_bf16 v[32:47], v[120:123], v[96:99], 0
	ds_read_b128 v[152:155], v196 offset:9216
	ds_read_b128 v[160:163], v196 offset:13824
	v_cvt_pk_bf16_f32 v176, v64, v65
	v_cvt_pk_bf16_f32 v177, v66, v67
	v_cvt_pk_bf16_f32 v178, v68, v69
	v_cvt_pk_bf16_f32 v179, v70, v71
	v_add_f32_e32 v174, v64, v174
	v_add_f32_e32 v175, v80, v175
	v_mfma_f32_32x32x16_bf16 v[48:63], v[128:131], v[96:99], 0
	ds_read_b128 v[156:159], v196 offset:9248
	ds_read_b128 v[164:167], v196 offset:13856
	v_cvt_pk_bf16_f32 v180, v72, v73
	v_cvt_pk_bf16_f32 v181, v74, v75
	v_cvt_pk_bf16_f32 v182, v76, v77
	v_cvt_pk_bf16_f32 v183, v78, v79
	v_add_f32_e32 v174, v65, v174
	v_add_f32_e32 v175, v81, v175
	v_mfma_f32_32x32x16_bf16 v[32:47], v[124:127], v[100:103], v[32:47]
	v_cvt_pk_bf16_f32 v184, v80, v81
	v_cvt_pk_bf16_f32 v185, v82, v83
	v_cvt_pk_bf16_f32 v186, v84, v85
	v_cvt_pk_bf16_f32 v187, v86, v87
	v_add_f32_e32 v174, v66, v174
	v_add_f32_e32 v175, v82, v175
	v_mfma_f32_32x32x16_bf16 v[48:63], v[132:135], v[100:103], v[48:63]
	v_cvt_pk_bf16_f32 v188, v88, v89
	v_cvt_pk_bf16_f32 v189, v90, v91
	v_cvt_pk_bf16_f32 v190, v92, v93
	v_cvt_pk_bf16_f32 v191, v94, v95
	v_add_f32_e32 v174, v67, v174
	v_add_f32_e32 v175, v83, v175
	v_mfma_f32_32x32x16_bf16 v[32:47], v[136:139], v[104:107], v[32:47]
	v_add_f32_e32 v174, v68, v174
	v_add_f32_e32 v175, v84, v175
	v_add_f32_e32 v174, v69, v174
	v_add_f32_e32 v175, v85, v175
	v_add_f32_e32 v174, v70, v174
	v_add_f32_e32 v175, v86, v175
	v_mfma_f32_32x32x16_bf16 v[48:63], v[144:147], v[104:107], v[48:63]
	v_add_f32_e32 v174, v71, v174
	v_add_f32_e32 v175, v87, v175
	v_add_f32_e32 v174, v72, v174
	v_add_f32_e32 v175, v88, v175
	v_add_f32_e32 v174, v73, v174
	v_add_f32_e32 v175, v89, v175
	v_mfma_f32_32x32x16_bf16 v[32:47], v[140:143], v[108:111], v[32:47]
	v_add_f32_e32 v174, v74, v174
	v_add_f32_e32 v175, v90, v175
	v_add_f32_e32 v174, v75, v174
	v_add_f32_e32 v175, v91, v175
	v_add_f32_e32 v174, v76, v174
	v_add_f32_e32 v175, v92, v175
	v_mfma_f32_32x32x16_bf16 v[48:63], v[148:151], v[108:111], v[48:63]
	v_add_f32_e32 v174, v77, v174
	v_add_f32_e32 v175, v93, v175
	v_add_f32_e32 v174, v78, v174
	v_add_f32_e32 v175, v94, v175
	v_add_f32_e32 v174, v79, v174
	v_add_f32_e32 v175, v95, v175
	ds_read_b128 v[120:123], v196 offset:9280
	ds_read_b128 v[124:127], v196 offset:13888
	ds_read_b128 v[128:131], v196 offset:9312
	ds_read_b128 v[132:135], v196 offset:13920
	s_andn2_b64 vcc, exec, s[38:39]
	s_cbranch_vccnz .LBB0_832
	s_nop 3
	v_sub_f32_e32 v47, v47, v200
	v_sub_f32_e32 v46, v46, v200
	v_sub_f32_e32 v45, v45, v200
	v_sub_f32_e32 v44, v44, v200
	v_sub_f32_e32 v43, v43, v200
	v_sub_f32_e32 v42, v42, v200
	v_sub_f32_e32 v41, v41, v200
	v_sub_f32_e32 v40, v40, v200
	v_sub_f32_e32 v39, v39, v200
	v_sub_f32_e32 v38, v38, v200
	v_sub_f32_e32 v37, v37, v200
	v_sub_f32_e32 v36, v36, v200
	v_sub_f32_e32 v35, v35, v200
	v_sub_f32_e32 v34, v34, v200
	v_sub_f32_e32 v33, v33, v200
	v_sub_f32_e32 v32, v32, v200
	v_sub_f32_e32 v63, v63, v200
	v_sub_f32_e32 v62, v62, v200
	v_sub_f32_e32 v61, v61, v200
	v_sub_f32_e32 v60, v60, v200
	v_sub_f32_e32 v59, v59, v200
	v_sub_f32_e32 v58, v58, v200
	v_sub_f32_e32 v57, v57, v200
	v_sub_f32_e32 v56, v56, v200
	v_sub_f32_e32 v55, v55, v200
	v_sub_f32_e32 v54, v54, v200
	v_sub_f32_e32 v53, v53, v200
	v_sub_f32_e32 v52, v52, v200
	v_sub_f32_e32 v51, v51, v200
	v_sub_f32_e32 v50, v50, v200
	v_sub_f32_e32 v49, v49, v200
	v_sub_f32_e32 v48, v48, v200
